# P8 requant pass: nt (streaming) loads for the read-once bf16 H tiles
# speedup vs baseline: 1.0110x; 1.0006x over previous
; #define GAS __attribute__((address_space(1)))
; __device__ __forceinline__ int q8u(float v) { int q = (int)rintf(v); q = q > 255 ? 255 : q; return (q < 0 ? 0 : q) - 128; }
; __device__ __forceinline__ unsigned pkq4(int a, int b, int c, int d) { return (unsigned)(a & 255) | ((unsigned)(b & 255) << 8) | ((unsigned)(c & 255) << 16) | ((unsigned)d << 24); }
; __device__ __forceinline__ void unpack8(v4u w, float (&f)[8]) { f[0] = bflo(w.x); f[1] = bfhi(w.x); f[2] = bflo(w.y); f[3] = bfhi(w.y); f[4] = bflo(w.z); f[5] = bfhi(w.z); f[6] = bflo(w.w); f[7] = bfhi(w.w); }
; __global__ void __launch_bounds__(NWAVES * 64, 2) enc_fwd(Args args) {
;     ...
;               for (int item = bx; item < (M / 256) * (FF / 128); item += G) { const int pm = item / (FF / 128), kk = item - pm * (FF / 128);
;                   const bf16* src = H + (((size_t)pm * (FF / 64) + kk * 2 + (b16 >> 2)) * 256 + r) * 64 + (b16 & 3) * 16; signed char* dst = HQ + (((size_t)pm * (FF / 128) + kk) * 256 + r) * 128 + b16 * 16;
;                   v4u lo[4], hi[4]; float inv[4];
; #pragma unroll
;                   for (int i = 0; i < 4; ++i) { lo[i] = *(const GAS v4u*)(src + i * 64 * 64); hi[i] = *(const GAS v4u*)(src + i * 64 * 64 + 8);
;                       const float tm = __uint_as_float(RMAX[pm * 256 + r + 64 * i]); inv[i] = 255.0f / fmaxf(tm * tm * 1.0078125f, 1e-30f); }
; #pragma unroll
;                   for (int i = 0; i < 4; ++i) { float a[8], b[8]; unpack8(lo[i], a); unpack8(hi[i], b); v4u o;
;                       o.x = pkq4(q8u(a[0] * inv[i]), q8u(a[1] * inv[i]), q8u(a[2] * inv[i]), q8u(a[3] * inv[i])); o.y = pkq4(q8u(a[4] * inv[i]), q8u(a[5] * inv[i]), q8u(a[6] * inv[i]), q8u(a[7] * inv[i]));
;                       o.z = pkq4(q8u(b[0] * inv[i]), q8u(b[1] * inv[i]), q8u(b[2] * inv[i]), q8u(b[3] * inv[i])); o.w = pkq4(q8u(b[4] * inv[i]), q8u(b[5] * inv[i]), q8u(b[6] * inv[i]), q8u(b[7] * inv[i]));
;                       *(GAS v4u*)(dst + i * 64 * 128) = o; } } }
.LBB0_800:
	s_ashr_i32 s2, s11, 31
	s_lshr_b32 s2, s2, 25
	s_add_i32 s3, s11, s2
	s_ashr_i32 s2, s3, 7
	s_lshl_b32 s7, s2, 8
	s_and_b32 s6, s3, 0xffffff80
	s_ashr_i32 s3, s2, 31
	s_sub_i32 s12, s10, s7
	s_lshl_b64 s[8:9], s[2:3], 8
	s_ashr_i32 s13, s12, 31
	s_add_u32 s8, s8, s12
	s_addc_u32 s9, s9, s13
	v_mov_b32_e32 v3, s9
	v_or_b32_e32 v2, s8, v36
	v_lshlrev_b64 v[2:3], 15, v[2:3]
	v_lshl_add_u64 v[26:27], v[38:39], 0, v[2:3]
	v_add_u32_e32 v2, s7, v34
	v_ashrrev_i32_e32 v3, 31, v2
	v_lshl_add_u64 v[42:43], v[2:3], 2, s[42:43]
	global_load_dwordx4 v[10:13], v[26:27], off offset:16 nt
	global_load_dwordx4 v[14:17], v[26:27], off nt
	global_load_dword v1, v[42:43], off
	s_lshl_b64 s[8:9], s[2:3], 22
	s_ashr_i32 s7, s6, 31
	v_add_co_u32_e32 v4, vcc, s83, v26
	s_mov_b64 s[2:3], 0x4000
	v_lshl_add_u64 v[2:3], v[26:27], 0, s[24:25]
	v_addc_co_u32_e32 v5, vcc, 0, v27, vcc
	global_load_dwordx4 v[6:9], v[4:5], off nt
	v_add_co_u32_e32 v20, vcc, s77, v26
	global_load_dwordx4 v[2:5], v[2:3], off offset:16 nt
	v_lshl_add_u64 v[18:19], v[26:27], 0, s[2:3]
	global_load_dword v56, v[42:43], off offset:256
	v_addc_co_u32_e32 v21, vcc, 0, v27, vcc
	s_mov_b64 s[2:3], 0x6000
	global_load_dwordx4 v[22:25], v[20:21], off nt
	s_nop 0
	global_load_dwordx4 v[18:21], v[18:19], off offset:16 nt
	global_load_dword v62, v[42:43], off offset:512
	v_lshl_add_u64 v[28:29], v[26:27], 0, s[2:3]
	s_movk_i32 s2, 0x6000
	v_add_co_u32_e32 v26, vcc, s2, v26
	s_nop 1
	v_addc_co_u32_e32 v27, vcc, 0, v27, vcc
	global_load_dwordx4 v[30:33], v[26:27], off nt
	s_nop 0
	global_load_dwordx4 v[26:29], v[28:29], off offset:16 nt
	global_load_dword v42, v[42:43], off offset:768
	s_waitcnt vmcnt(0)
	v_lshlrev_b32_e32 v49, 16, v10
	v_and_b32_e32 v50, 0xffff0000, v10
	v_mul_f32_e32 v1, v1, v1
	v_mul_f32_e32 v1, 0x3f810000, v1
	v_max_f32_e32 v1, 0xda24260, v1
	v_div_scale_f32 v57, s[2:3], v1, v1, s56
	v_rcp_f32_e32 v58, v57
	v_lshlrev_b32_e32 v51, 16, v11
	v_and_b32_e32 v52, 0xffff0000, v11
	v_lshlrev_b32_e32 v53, 16, v12
	v_fma_f32 v59, -v57, v58, 1.0
	v_fmac_f32_e32 v58, v59, v58
	v_div_scale_f32 v59, vcc, s56, v1, s56
	v_mul_f32_e32 v60, v59, v58
	v_fma_f32 v61, -v57, v60, v59
	v_fmac_f32_e32 v60, v61, v58
	v_fma_f32 v57, -v57, v60, v59
	v_div_fmas_f32 v57, v57, v58, v60
	v_div_fixup_f32 v35, v57, v1, s56
	v_and_b32_e32 v54, 0xffff0000, v12
	v_lshlrev_b32_e32 v48, 16, v17
	v_and_b32_e32 v17, 0xffff0000, v17
	v_lshlrev_b32_e32 v55, 16, v13
	v_and_b32_e32 v13, 0xffff0000, v13
	v_mul_f32_e32 v13, v35, v13
	v_rndne_f32_e32 v13, v13
	v_cvt_i32_f32_e32 v13, v13
	v_med3_i32 v13, v13, 0, v212
	v_lshlrev_b32_e32 v13, 24, v13
	v_mul_f32_e32 v1, v56, v56
	v_mul_f32_e32 v1, 0x3f810000, v1
	v_max_f32_e32 v1, 0xda24260, v1
	v_div_scale_f32 v57, s[2:3], v1, v1, s56
	v_rcp_f32_e32 v58, v57
	s_nop 0
	v_fma_f32 v59, -v57, v58, 1.0
	v_fmac_f32_e32 v58, v59, v58
	v_div_scale_f32 v59, vcc, s56, v1, s56
	v_mul_f32_e32 v60, v59, v58
	v_fma_f32 v61, -v57, v60, v59
	v_fmac_f32_e32 v60, v61, v58
	v_fma_f32 v57, -v57, v60, v59
	v_div_fmas_f32 v57, v57, v58, v60
	v_div_fixup_f32 v1, v57, v1, s56
	v_mul_f32_e32 v62, v62, v62
	v_mul_f32_e32 v62, 0x3f810000, v62
	v_max_f32_e32 v62, 0xda24260, v62
	v_div_scale_f32 v57, s[2:3], v62, v62, s56
	v_rcp_f32_e32 v58, v57
	s_nop 0
	v_fma_f32 v59, -v57, v58, 1.0
	v_fmac_f32_e32 v58, v59, v58
	v_div_scale_f32 v59, vcc, s56, v62, s56
	v_mul_f32_e32 v60, v59, v58
	v_fma_f32 v61, -v57, v60, v59
	v_fmac_f32_e32 v60, v61, v58
	v_fma_f32 v57, -v57, v60, v59
	v_div_fmas_f32 v57, v57, v58, v60
	v_div_fixup_f32 v37, v57, v62, s56
	v_mul_f32_e32 v42, v42, v42
	v_mul_f32_e32 v42, 0x3f810000, v42
	v_max_f32_e32 v42, 0xda24260, v42
	v_div_scale_f32 v43, s[2:3], v42, v42, s56
	v_rcp_f32_e32 v44, v43
	s_lshl_b64 s[2:3], s[6:7], 15
	s_sub_u32 s2, s8, s2
	s_subb_u32 s3, s9, s3
	v_fma_f32 v45, -v43, v44, 1.0
	v_fmac_f32_e32 v44, v45, v44
	v_div_scale_f32 v45, vcc, s56, v42, s56
	v_mul_f32_e32 v46, v45, v44
	v_fma_f32 v47, -v43, v46, v45
	v_fmac_f32_e32 v46, v47, v44
	v_fma_f32 v43, -v43, v46, v45
	v_lshlrev_b32_e32 v45, 16, v14
	v_and_b32_e32 v14, 0xffff0000, v14
	v_div_fmas_f32 v43, v43, v44, v46
	v_lshlrev_b32_e32 v46, 16, v15
	v_and_b32_e32 v15, 0xffff0000, v15
	v_mul_f32_e32 v10, v35, v45
	v_mul_f32_e32 v11, v35, v14
	v_rndne_f32_e32 v10, v10
	v_rndne_f32_e32 v11, v11
	v_mul_f32_e32 v12, v35, v46
	v_mul_f32_e32 v14, v35, v15
	v_cvt_i32_f32_e32 v10, v10
	v_cvt_i32_f32_e32 v11, v11
	v_rndne_f32_e32 v12, v12
	v_rndne_f32_e32 v14, v14
	v_cvt_i32_f32_e32 v12, v12
	v_cvt_i32_f32_e32 v14, v14
	v_med3_i32 v10, v10, 0, v212
	v_med3_i32 v11, v11, 0, v212
	v_lshlrev_b32_e32 v47, 16, v16
	v_and_b32_e32 v16, 0xffff0000, v16
	v_med3_i32 v12, v12, 0, v212
	v_med3_i32 v14, v14, 0, v212
	v_lshl_or_b32 v10, v11, 8, v10
	v_lshl_or_b32 v10, v12, 16, v10
	v_lshlrev_b32_e32 v11, 24, v14
	v_mul_f32_e32 v12, v35, v16
	v_mul_f32_e32 v14, v35, v48
	v_bitop3_b32 v10, v10, s57, v11 bitop3:0x36
	v_mul_f32_e32 v11, v35, v47
	v_rndne_f32_e32 v12, v12
	v_rndne_f32_e32 v14, v14
	v_mul_f32_e32 v15, v35, v17
	v_rndne_f32_e32 v11, v11
	v_cvt_i32_f32_e32 v12, v12
	v_cvt_i32_f32_e32 v14, v14
	v_rndne_f32_e32 v15, v15
	v_cvt_i32_f32_e32 v11, v11
	v_cvt_i32_f32_e32 v15, v15
	v_med3_i32 v12, v12, 0, v212
	v_med3_i32 v14, v14, 0, v212
	v_med3_i32 v11, v11, 0, v212
	v_med3_i32 v15, v15, 0, v212
	v_lshlrev_b32_e32 v12, 8, v12
	v_lshlrev_b32_e32 v14, 16, v14
	v_or3_b32 v11, v12, v11, v14
	v_lshlrev_b32_e32 v12, 24, v15
	v_bitop3_b32 v11, v11, s57, v12 bitop3:0x36
	v_mul_f32_e32 v12, v35, v49
	v_mul_f32_e32 v14, v35, v50
	v_rndne_f32_e32 v12, v12
	v_rndne_f32_e32 v14, v14
	v_mul_f32_e32 v15, v35, v51
	v_mul_f32_e32 v16, v35, v52
; #define GAS __attribute__((address_space(1)))
; __device__ __forceinline__ int q8u(float v) { int q = (int)rintf(v); q = q > 255 ? 255 : q; return (q < 0 ? 0 : q) - 128; }
; __device__ __forceinline__ unsigned pkq4(int a, int b, int c, int d) { return (unsigned)(a & 255) | ((unsigned)(b & 255) << 8) | ((unsigned)(c & 255) << 16) | ((unsigned)d << 24); }
; __device__ __forceinline__ void unpack8(v4u w, float (&f)[8]) { f[0] = bflo(w.x); f[1] = bfhi(w.x); f[2] = bflo(w.y); f[3] = bfhi(w.y); f[4] = bflo(w.z); f[5] = bfhi(w.z); f[6] = bflo(w.w); f[7] = bfhi(w.w); }
; __global__ void __launch_bounds__(NWAVES * 64, 2) enc_fwd(Args args) {
;     ...
; #pragma unroll
;                   for (int i = 0; i < 4; ++i) { float a[8], b[8]; unpack8(lo[i], a); unpack8(hi[i], b); v4u o;
;                       o.x = pkq4(q8u(a[0] * inv[i]), q8u(a[1] * inv[i]), q8u(a[2] * inv[i]), q8u(a[3] * inv[i])); o.y = pkq4(q8u(a[4] * inv[i]), q8u(a[5] * inv[i]), q8u(a[6] * inv[i]), q8u(a[7] * inv[i]));
;                       o.z = pkq4(q8u(b[0] * inv[i]), q8u(b[1] * inv[i]), q8u(b[2] * inv[i]), q8u(b[3] * inv[i])); o.w = pkq4(q8u(b[4] * inv[i]), q8u(b[5] * inv[i]), q8u(b[6] * inv[i]), q8u(b[7] * inv[i]));
;                       *(GAS v4u*)(dst + i * 64 * 128) = o; } } }
	v_cvt_i32_f32_e32 v12, v12
	v_cvt_i32_f32_e32 v14, v14
	v_rndne_f32_e32 v15, v15
	v_rndne_f32_e32 v16, v16
	v_cvt_i32_f32_e32 v15, v15
	v_cvt_i32_f32_e32 v16, v16
	v_med3_i32 v12, v12, 0, v212
	v_med3_i32 v14, v14, 0, v212
	v_med3_i32 v15, v15, 0, v212
	v_med3_i32 v16, v16, 0, v212
	v_lshl_or_b32 v12, v14, 8, v12
	v_lshl_or_b32 v12, v15, 16, v12
	v_lshlrev_b32_e32 v14, 24, v16
	v_mul_f32_e32 v15, v35, v54
	v_mul_f32_e32 v16, v35, v55
	v_bitop3_b32 v12, v12, s57, v14 bitop3:0x36
	v_mul_f32_e32 v14, v35, v53
	v_rndne_f32_e32 v15, v15
	v_rndne_f32_e32 v16, v16
	v_rndne_f32_e32 v14, v14
	v_cvt_i32_f32_e32 v15, v15
	v_cvt_i32_f32_e32 v16, v16
	v_cvt_i32_f32_e32 v14, v14
	v_div_fixup_f32 v44, v43, v42, s56
	v_med3_i32 v15, v15, 0, v212
	v_med3_i32 v16, v16, 0, v212
	v_med3_i32 v14, v14, 0, v212
	v_lshlrev_b32_e32 v15, 8, v15
	v_lshlrev_b32_e32 v16, 16, v16
	v_or3_b32 v14, v15, v14, v16
	v_lshl_add_u64 v[42:43], v[40:41], 0, s[2:3]
	v_bitop3_b32 v13, v14, s57, v13 bitop3:0x36
	global_store_dwordx4 v[42:43], v[10:13], off
	v_lshlrev_b32_e32 v14, 16, v2
	v_and_b32_e32 v15, 0xffff0000, v2
	v_lshlrev_b32_e32 v10, 16, v6
	v_and_b32_e32 v6, 0xffff0000, v6
	v_lshlrev_b32_e32 v11, 16, v7
	v_and_b32_e32 v7, 0xffff0000, v7
	v_lshlrev_b32_e32 v16, 16, v3
	v_and_b32_e32 v17, 0xffff0000, v3
	v_mul_f32_e32 v2, v1, v10
	v_mul_f32_e32 v3, v1, v6
	v_lshlrev_b32_e32 v35, 16, v4
	v_and_b32_e32 v45, 0xffff0000, v4
	v_rndne_f32_e32 v2, v2
	v_rndne_f32_e32 v3, v3
	v_mul_f32_e32 v4, v1, v11
	v_mul_f32_e32 v6, v1, v7
	v_cvt_i32_f32_e32 v2, v2
	v_cvt_i32_f32_e32 v3, v3
	v_rndne_f32_e32 v4, v4
	v_rndne_f32_e32 v6, v6
	v_cvt_i32_f32_e32 v4, v4
	v_cvt_i32_f32_e32 v6, v6
	v_med3_i32 v2, v2, 0, v212
	v_med3_i32 v3, v3, 0, v212
	v_lshlrev_b32_e32 v12, 16, v8
	v_and_b32_e32 v8, 0xffff0000, v8
	v_lshlrev_b32_e32 v13, 16, v9
	v_med3_i32 v4, v4, 0, v212
	v_med3_i32 v6, v6, 0, v212
	v_lshl_or_b32 v2, v3, 8, v2
	v_and_b32_e32 v9, 0xffff0000, v9
	v_lshl_or_b32 v2, v4, 16, v2
	v_lshlrev_b32_e32 v3, 24, v6
	v_mul_f32_e32 v4, v1, v8
	v_mul_f32_e32 v6, v1, v13
	v_bitop3_b32 v2, v2, s57, v3 bitop3:0x36
	v_mul_f32_e32 v3, v1, v12
	v_rndne_f32_e32 v4, v4
	v_rndne_f32_e32 v6, v6
	v_mul_f32_e32 v7, v1, v9
	v_rndne_f32_e32 v3, v3
	v_cvt_i32_f32_e32 v4, v4
	v_cvt_i32_f32_e32 v6, v6
	v_rndne_f32_e32 v7, v7
	v_cvt_i32_f32_e32 v3, v3
	v_cvt_i32_f32_e32 v7, v7
	v_med3_i32 v4, v4, 0, v212
	v_med3_i32 v6, v6, 0, v212
	v_med3_i32 v3, v3, 0, v212
	v_med3_i32 v7, v7, 0, v212
	v_lshlrev_b32_e32 v4, 8, v4
	v_lshlrev_b32_e32 v6, 16, v6
	v_or3_b32 v3, v4, v3, v6
	v_lshlrev_b32_e32 v4, 24, v7
	v_bitop3_b32 v3, v3, s57, v4 bitop3:0x36
	v_mul_f32_e32 v4, v1, v14
	v_mul_f32_e32 v6, v1, v15
	v_rndne_f32_e32 v4, v4
	v_rndne_f32_e32 v6, v6
	v_mul_f32_e32 v7, v1, v16
	v_mul_f32_e32 v8, v1, v17
	v_cvt_i32_f32_e32 v4, v4
	v_cvt_i32_f32_e32 v6, v6
	v_rndne_f32_e32 v7, v7
	v_rndne_f32_e32 v8, v8
	v_cvt_i32_f32_e32 v7, v7
	v_cvt_i32_f32_e32 v8, v8
	v_med3_i32 v4, v4, 0, v212
	v_med3_i32 v6, v6, 0, v212
	v_lshlrev_b32_e32 v46, 16, v5
	v_med3_i32 v7, v7, 0, v212
	v_med3_i32 v8, v8, 0, v212
	v_lshl_or_b32 v4, v6, 8, v4
	v_and_b32_e32 v5, 0xffff0000, v5
	v_lshl_or_b32 v4, v7, 16, v4
	v_lshlrev_b32_e32 v6, 24, v8
	v_mul_f32_e32 v7, v1, v45
	v_mul_f32_e32 v8, v1, v46
	v_bitop3_b32 v4, v4, s57, v6 bitop3:0x36
	v_mul_f32_e32 v6, v1, v35
	v_rndne_f32_e32 v7, v7
	v_rndne_f32_e32 v8, v8
	v_mul_f32_e32 v1, v1, v5
	v_rndne_f32_e32 v6, v6
	v_cvt_i32_f32_e32 v7, v7
	v_cvt_i32_f32_e32 v8, v8
	v_rndne_f32_e32 v1, v1
	v_cvt_i32_f32_e32 v6, v6
	v_cvt_i32_f32_e32 v1, v1
	v_med3_i32 v7, v7, 0, v212
	v_med3_i32 v8, v8, 0, v212
	v_med3_i32 v6, v6, 0, v212
	v_med3_i32 v1, v1, 0, v212
	v_lshlrev_b32_e32 v5, 8, v7
	v_lshlrev_b32_e32 v7, 16, v8
	v_or3_b32 v5, v5, v6, v7
	v_lshlrev_b32_e32 v1, 24, v1
	v_add_co_u32_e32 v6, vcc, s83, v42
	v_bitop3_b32 v5, v5, s57, v1 bitop3:0x36
	s_nop 0
	v_addc_co_u32_e32 v7, vcc, 0, v43, vcc
	global_store_dwordx4 v[6:7], v[2:5], off
	v_lshlrev_b32_e32 v1, 16, v22
	v_mul_f32_e32 v1, v37, v1
	v_and_b32_e32 v2, 0xffff0000, v22
	v_lshlrev_b32_e32 v3, 16, v23
	v_and_b32_e32 v4, 0xffff0000, v23
	v_mul_f32_e32 v2, v37, v2
	v_rndne_f32_e32 v1, v1
	v_rndne_f32_e32 v2, v2
	v_mul_f32_e32 v3, v37, v3
	v_mul_f32_e32 v4, v37, v4
	v_cvt_i32_f32_e32 v1, v1
	v_cvt_i32_f32_e32 v2, v2
	v_rndne_f32_e32 v3, v3
	v_rndne_f32_e32 v4, v4
	v_cvt_i32_f32_e32 v3, v3
	v_cvt_i32_f32_e32 v4, v4
	v_med3_i32 v1, v1, 0, v212
	v_med3_i32 v2, v2, 0, v212
	v_and_b32_e32 v6, 0xffff0000, v24
	v_lshlrev_b32_e32 v7, 16, v25
	v_med3_i32 v3, v3, 0, v212
	v_med3_i32 v4, v4, 0, v212
	v_lshl_or_b32 v1, v2, 8, v1
	v_lshlrev_b32_e32 v5, 16, v24
	v_and_b32_e32 v8, 0xffff0000, v25
	v_lshl_or_b32 v1, v3, 16, v1
	v_lshlrev_b32_e32 v2, 24, v4
	v_mul_f32_e32 v3, v37, v6
	v_mul_f32_e32 v4, v37, v7
	v_bitop3_b32 v2, v1, s57, v2 bitop3:0x36
	v_mul_f32_e32 v1, v37, v5
	v_rndne_f32_e32 v3, v3
	v_rndne_f32_e32 v4, v4
	v_mul_f32_e32 v5, v37, v8
	v_rndne_f32_e32 v1, v1
	v_cvt_i32_f32_e32 v3, v3
; #define GAS __attribute__((address_space(1)))
; __device__ __forceinline__ int q8u(float v) { int q = (int)rintf(v); q = q > 255 ? 255 : q; return (q < 0 ? 0 : q) - 128; }
; __device__ __forceinline__ unsigned pkq4(int a, int b, int c, int d) { return (unsigned)(a & 255) | ((unsigned)(b & 255) << 8) | ((unsigned)(c & 255) << 16) | ((unsigned)d << 24); }
; __device__ __forceinline__ void unpack8(v4u w, float (&f)[8]) { f[0] = bflo(w.x); f[1] = bfhi(w.x); f[2] = bflo(w.y); f[3] = bfhi(w.y); f[4] = bflo(w.z); f[5] = bfhi(w.z); f[6] = bflo(w.w); f[7] = bfhi(w.w); }
; __global__ void __launch_bounds__(NWAVES * 64, 2) enc_fwd(Args args) {
;     ...
; #pragma unroll
;                   for (int i = 0; i < 4; ++i) { float a[8], b[8]; unpack8(lo[i], a); unpack8(hi[i], b); v4u o;
;                       o.x = pkq4(q8u(a[0] * inv[i]), q8u(a[1] * inv[i]), q8u(a[2] * inv[i]), q8u(a[3] * inv[i])); o.y = pkq4(q8u(a[4] * inv[i]), q8u(a[5] * inv[i]), q8u(a[6] * inv[i]), q8u(a[7] * inv[i]));
;                       o.z = pkq4(q8u(b[0] * inv[i]), q8u(b[1] * inv[i]), q8u(b[2] * inv[i]), q8u(b[3] * inv[i])); o.w = pkq4(q8u(b[4] * inv[i]), q8u(b[5] * inv[i]), q8u(b[6] * inv[i]), q8u(b[7] * inv[i]));
;                       *(GAS v4u*)(dst + i * 64 * 128) = o; } } }
	v_cvt_i32_f32_e32 v4, v4
	v_rndne_f32_e32 v5, v5
	v_cvt_i32_f32_e32 v1, v1
	v_cvt_i32_f32_e32 v5, v5
	v_med3_i32 v3, v3, 0, v212
	v_med3_i32 v4, v4, 0, v212
	v_med3_i32 v1, v1, 0, v212
	v_med3_i32 v5, v5, 0, v212
	v_lshlrev_b32_e32 v3, 8, v3
	v_lshlrev_b32_e32 v4, 16, v4
	v_lshlrev_b32_e32 v9, 16, v18
	v_and_b32_e32 v10, 0xffff0000, v18
	v_or3_b32 v1, v3, v1, v4
	v_lshlrev_b32_e32 v3, 24, v5
	v_lshlrev_b32_e32 v11, 16, v19
	v_and_b32_e32 v12, 0xffff0000, v19
	v_bitop3_b32 v3, v1, s57, v3 bitop3:0x36
	v_mul_f32_e32 v1, v37, v9
	v_mul_f32_e32 v4, v37, v10
	v_rndne_f32_e32 v1, v1
	v_rndne_f32_e32 v4, v4
	v_mul_f32_e32 v5, v37, v11
	v_mul_f32_e32 v6, v37, v12
	v_cvt_i32_f32_e32 v1, v1
	v_cvt_i32_f32_e32 v4, v4
	v_rndne_f32_e32 v5, v5
	v_rndne_f32_e32 v6, v6
	v_cvt_i32_f32_e32 v5, v5
	v_cvt_i32_f32_e32 v6, v6
	v_med3_i32 v1, v1, 0, v212
	v_med3_i32 v4, v4, 0, v212
	v_and_b32_e32 v14, 0xffff0000, v20
	v_lshlrev_b32_e32 v15, 16, v21
	v_med3_i32 v5, v5, 0, v212
	v_med3_i32 v6, v6, 0, v212
	v_lshl_or_b32 v1, v4, 8, v1
	v_lshlrev_b32_e32 v13, 16, v20
	v_and_b32_e32 v16, 0xffff0000, v21
	v_lshl_or_b32 v1, v5, 16, v1
	v_lshlrev_b32_e32 v4, 24, v6
	v_mul_f32_e32 v5, v37, v14
	v_mul_f32_e32 v6, v37, v15
	v_bitop3_b32 v4, v1, s57, v4 bitop3:0x36
	v_mul_f32_e32 v1, v37, v13
	v_rndne_f32_e32 v5, v5
	v_rndne_f32_e32 v6, v6
	v_mul_f32_e32 v7, v37, v16
	v_rndne_f32_e32 v1, v1
	v_cvt_i32_f32_e32 v5, v5
	v_cvt_i32_f32_e32 v6, v6
	v_rndne_f32_e32 v7, v7
	v_cvt_i32_f32_e32 v1, v1
	v_cvt_i32_f32_e32 v7, v7
	v_med3_i32 v5, v5, 0, v212
	v_med3_i32 v6, v6, 0, v212
	v_med3_i32 v1, v1, 0, v212
	v_med3_i32 v7, v7, 0, v212
	v_lshlrev_b32_e32 v5, 8, v5
	v_lshlrev_b32_e32 v6, 16, v6
	v_or3_b32 v1, v5, v1, v6
	v_lshlrev_b32_e32 v5, 24, v7
	v_add_co_u32_e32 v6, vcc, s77, v42
	v_bitop3_b32 v5, v1, s57, v5 bitop3:0x36
	s_nop 0
	v_addc_co_u32_e32 v7, vcc, 0, v43, vcc
	global_store_dwordx4 v[6:7], v[2:5], off
	v_lshlrev_b32_e32 v1, 16, v30
	v_mul_f32_e32 v1, v44, v1
	v_and_b32_e32 v2, 0xffff0000, v30
	v_lshlrev_b32_e32 v3, 16, v31
	v_and_b32_e32 v4, 0xffff0000, v31
	v_mul_f32_e32 v2, v44, v2
	v_rndne_f32_e32 v1, v1
	v_rndne_f32_e32 v2, v2
	v_mul_f32_e32 v3, v44, v3
	v_mul_f32_e32 v4, v44, v4
	v_cvt_i32_f32_e32 v1, v1
	v_cvt_i32_f32_e32 v2, v2
	v_rndne_f32_e32 v3, v3
	v_rndne_f32_e32 v4, v4
	v_cvt_i32_f32_e32 v3, v3
	v_cvt_i32_f32_e32 v4, v4
	v_med3_i32 v1, v1, 0, v212
	v_med3_i32 v2, v2, 0, v212
	v_and_b32_e32 v6, 0xffff0000, v32
	v_lshlrev_b32_e32 v7, 16, v33
	v_med3_i32 v3, v3, 0, v212
	v_med3_i32 v4, v4, 0, v212
	v_lshl_or_b32 v1, v2, 8, v1
	v_lshlrev_b32_e32 v5, 16, v32
	v_and_b32_e32 v8, 0xffff0000, v33
	v_lshl_or_b32 v1, v3, 16, v1
	v_lshlrev_b32_e32 v2, 24, v4
	v_mul_f32_e32 v3, v44, v6
	v_mul_f32_e32 v4, v44, v7
	v_bitop3_b32 v2, v1, s57, v2 bitop3:0x36
	v_mul_f32_e32 v1, v44, v5
	v_rndne_f32_e32 v3, v3
	v_rndne_f32_e32 v4, v4
	v_mul_f32_e32 v5, v44, v8
	v_rndne_f32_e32 v1, v1
	v_cvt_i32_f32_e32 v3, v3
	v_cvt_i32_f32_e32 v4, v4
	v_rndne_f32_e32 v5, v5
	v_cvt_i32_f32_e32 v1, v1
	v_cvt_i32_f32_e32 v5, v5
	v_med3_i32 v3, v3, 0, v212
	v_med3_i32 v4, v4, 0, v212
	v_med3_i32 v1, v1, 0, v212
	v_med3_i32 v5, v5, 0, v212
	v_lshlrev_b32_e32 v3, 8, v3
	v_lshlrev_b32_e32 v4, 16, v4
	v_lshlrev_b32_e32 v9, 16, v26
	v_and_b32_e32 v10, 0xffff0000, v26
	v_or3_b32 v1, v3, v1, v4
	v_lshlrev_b32_e32 v3, 24, v5
	v_lshlrev_b32_e32 v11, 16, v27
	v_and_b32_e32 v12, 0xffff0000, v27
	v_bitop3_b32 v3, v1, s57, v3 bitop3:0x36
	v_mul_f32_e32 v1, v44, v9
	v_mul_f32_e32 v4, v44, v10
	v_rndne_f32_e32 v1, v1
	v_rndne_f32_e32 v4, v4
	v_mul_f32_e32 v5, v44, v11
	v_mul_f32_e32 v6, v44, v12
	v_cvt_i32_f32_e32 v1, v1
	v_cvt_i32_f32_e32 v4, v4
	v_rndne_f32_e32 v5, v5
	v_rndne_f32_e32 v6, v6
	v_cvt_i32_f32_e32 v5, v5
	v_cvt_i32_f32_e32 v6, v6
	v_med3_i32 v1, v1, 0, v212
	v_med3_i32 v4, v4, 0, v212
	v_and_b32_e32 v14, 0xffff0000, v28
	v_lshlrev_b32_e32 v15, 16, v29
	v_med3_i32 v5, v5, 0, v212
	v_med3_i32 v6, v6, 0, v212
	v_lshl_or_b32 v1, v4, 8, v1
	v_lshlrev_b32_e32 v13, 16, v28
	v_and_b32_e32 v16, 0xffff0000, v29
	v_lshl_or_b32 v1, v5, 16, v1
	v_lshlrev_b32_e32 v4, 24, v6
	v_mul_f32_e32 v5, v44, v14
	v_mul_f32_e32 v6, v44, v15
	v_bitop3_b32 v4, v1, s57, v4 bitop3:0x36
	v_mul_f32_e32 v1, v44, v13
	v_rndne_f32_e32 v5, v5
	v_rndne_f32_e32 v6, v6
	v_mul_f32_e32 v7, v44, v16
	v_rndne_f32_e32 v1, v1
	v_cvt_i32_f32_e32 v5, v5
	v_cvt_i32_f32_e32 v6, v6
	v_rndne_f32_e32 v7, v7
	v_cvt_i32_f32_e32 v1, v1
	v_cvt_i32_f32_e32 v7, v7
	v_med3_i32 v5, v5, 0, v212
	v_med3_i32 v6, v6, 0, v212
	v_med3_i32 v1, v1, 0, v212
	v_med3_i32 v7, v7, 0, v212
	v_lshlrev_b32_e32 v5, 8, v5
	v_lshlrev_b32_e32 v6, 16, v6
	v_or3_b32 v1, v5, v1, v6
	v_lshlrev_b32_e32 v5, 24, v7
	v_add_co_u32_e32 v6, vcc, 0x6000, v42
	s_add_i32 s11, s11, s86
	s_add_i32 s10, s10, s29
	v_bitop3_b32 v5, v1, s57, v5 bitop3:0x36
	v_addc_co_u32_e32 v7, vcc, 0, v43, vcc
	v_lshl_add_u64 v[40:41], v[40:41], 0, s[68:69]
	s_cmpk_gt_i32 s11, 0x1fff
	global_store_dwordx4 v[6:7], v[2:5], off
	s_cbranch_scc0 .LBB0_800
